# workgroups 0..63: the norm-counter wait that replaces the mixer-in barrier release also moved into their gMLP GEMM preamble (after its weight-tile loads)
# baseline (speedup 1.0000x reference)
.LBB0_939:
	s_or_b64 exec, exec, s[12:13]
	v_cvt_f32_u32_e32 v4, v2
	s_waitcnt vmcnt(0)
	v_readfirstlane_b32 s2, v3
	v_sub_u32_e32 v3, 0, v2
	v_rcp_iflag_f32_e32 v4, v4
	v_add_u32_e32 v5, s2, v1
	v_mul_f32_e32 v4, 0x4f7ffffe, v4
	v_cvt_u32_f32_e32 v4, v4
	v_mul_lo_u32 v1, v3, v4
	v_mul_hi_u32 v1, v4, v1
	v_add_u32_e32 v1, v4, v1
	v_mul_hi_u32 v1, v5, v1
	v_mul_lo_u32 v3, v1, v2
	v_sub_u32_e32 v3, v5, v3
	v_add_u32_e32 v4, 1, v1
	v_cmp_ge_u32_e32 vcc, v3, v2
	s_nop 1
	v_cndmask_b32_e32 v1, v1, v4, vcc
	v_sub_u32_e32 v4, v3, v2
	v_cndmask_b32_e32 v3, v3, v4, vcc
	v_add_u32_e32 v4, 1, v1
	v_cmp_ge_u32_e32 vcc, v3, v2
	v_add_u32_e32 v3, 1, v5
	s_nop 0
	v_cndmask_b32_e32 v1, v1, v4, vcc
	v_mul_lo_u32 v4, v2, v1
	v_add_u32_e32 v2, v4, v2
	v_cmp_ne_u32_e32 vcc, v3, v2
	s_and_saveexec_b64 s[10:11], vcc
	s_xor_b64 s[10:11], exec, s[10:11]
	s_cbranch_execz .LBB0_953
	v_readlane_b32 s18, v255, 0
	s_nop 0
	s_cmp_lt_u32 s18, 64
	s_cbranch_scc0 .Lb5_std
	s_and_b32 s18, s18, 31
	s_lshl_b32 s18, s18, 7
	s_add_u32 s18, s18, 0xb000
	v_readlane_b32 s19, v255, 47
	s_waitcnt lgkmcnt(0)
	v_writelane_b32 v255, s18, 50
	v_writelane_b32 v255, s19, 51
	v_writelane_b32 v255, s18, 52
	v_writelane_b32 v255, s19, 53
	v_writelane_b32 v255, s6, 54
	v_writelane_b32 v255, s7, 55
	s_branch .Lb5_join
	v_mov_b32_e32 v0, s18
	s_mov_b32 s2, 0
	s_waitcnt lgkmcnt(0)

.LBB0_992:
	s_ashr_i32 s71, s20, 6
	v_and_b32_e32 v128, 63, v166
	s_andn2_b64 vcc, exec, s[6:7]
	s_mulk_i32 s71, 0x4400
	s_cbranch_vccnz .LBB0_1021
	v_mov_b32_e32 v11, v147
	s_cmp_lt_i32 s2, 0
	v_readfirstlane_b32 s18, v11
	s_cbranch_scc1 .LBB0_1001
	v_lshlrev_b32_e32 v0, 4, v11
	v_add_u32_e32 v1, 0x2000, v0
	v_ashrrev_i32_e32 v2, 31, v1
	v_lshrrev_b32_e32 v2, 22, v2
	v_add_u32_e32 v2, v1, v2
	v_ashrrev_i32_e32 v8, 10, v2
	v_mul_i32_i24_e32 v2, 0x400, v8
	v_sub_u32_e32 v1, v1, v2
	v_lshrrev_b32_e32 v2, 4, v1
	v_bitop3_b32 v1, v2, v1, 32 bitop3:0x6c
	v_ashrrev_i32_e32 v2, 31, v1
	v_lshrrev_b32_e32 v2, 26, v2
	v_add_u32_e32 v2, v1, v2
	v_lshlrev_b32_e32 v3, 3, v8
	s_ashr_i32 s12, s18, 6
	v_ashrrev_i32_e32 v9, 6, v2
	v_and_b32_e32 v3, -16, v3
	s_ashr_i32 s13, s18, 8
	s_lshl_b32 s19, s12, 10
	s_mul_i32 s6, s70, 0x2800000
	v_add_u32_e32 v3, v9, v3
	s_waitcnt lgkmcnt(0)
	s_add_u32 s8, s4, s6
	v_and_b32_e32 v4, 3, v9
	s_mov_b32 s6, 0x1fffe0
	v_lshrrev_b32_e32 v5, 2, v3
	v_lshlrev_b32_e32 v6, 1, v3
	v_and_b32_e32 v2, 0xc0, v2
	v_and_or_b32 v4, v3, s6, v4
	v_and_b32_e32 v5, 4, v5
	v_and_b32_e32 v6, 24, v6
	v_sub_u32_e32 v1, v1, v2
	v_or3_b32 v4, v4, v5, v6
	v_lshlrev_b32_e32 v5, 5, v8
	v_ashrrev_i16_sdwa v1, v189, sext(v1) dst_sel:DWORD dst_unused:UNUSED_PAD src0_sel:DWORD src1_sel:BYTE_0
	v_and_b32_e32 v5, 32, v5
	v_bfe_i32 v10, v1, 0, 16
	v_add_lshl_u32 v1, v5, v10, 1
	v_lshl_add_u32 v130, v4, 11, v1
	v_lshl_add_u32 v132, v3, 11, v1
	v_bfe_i32 v1, v11, 27, 1
	v_lshrrev_b32_e32 v1, 22, v1
	v_add_u32_e32 v1, v0, v1
	v_and_b32_e32 v1, 0xfffffc00, v1
	v_sub_u32_e32 v0, v0, v1
	v_lshrrev_b32_e32 v1, 4, v0
	v_bitop3_b32 v1, v1, v0, 32 bitop3:0x6c
	v_ashrrev_i32_e32 v0, 31, v0
	v_lshrrev_b32_e32 v0, 26, v0
	v_add_u32_e32 v0, v1, v0
	v_ashrrev_i32_e32 v12, 6, v0
	v_ashrrev_i32_e32 v0, 31, v11
	v_lshrrev_b32_e32 v0, 26, v0
	v_add_u32_e32 v0, v11, v0
	v_ashrrev_i32_e32 v13, 6, v0
	v_lshlrev_b32_e32 v0, 3, v13
	v_and_b32_e32 v0, -16, v0
	v_add_u32_e32 v0, v12, v0
	v_and_b32_e32 v2, 3, v12
	v_lshrrev_b32_e32 v3, 2, v0
	v_lshlrev_b32_e32 v4, 1, v0
	v_and_or_b32 v2, v0, s6, v2
	v_and_b32_e32 v3, 4, v3
	v_and_b32_e32 v4, 24, v4
	v_or3_b32 v2, v2, v3, v4
	v_mul_i32_i24_e32 v4, 64, v12
	v_sub_u32_e32 v1, v1, v4
	v_lshlrev_b32_e32 v3, 5, v13
	v_ashrrev_i16_sdwa v1, v189, sext(v1) dst_sel:DWORD dst_unused:UNUSED_PAD src0_sel:DWORD src1_sel:BYTE_0
	v_and_b32_e32 v3, 32, v3
	v_bfe_i32 v14, v1, 0, 16
	v_add_lshl_u32 v1, v3, v14, 1
	s_addc_u32 s9, s5, 0
	v_lshl_add_u32 v134, v0, 11, v1
	v_sub_co_u32_e64 v0, s[6:7], s2, 32
	s_and_b64 s[6:7], s[6:7], exec
	v_readfirstlane_b32 s6, v0
	s_cselect_b32 s38, s2, s6
	s_cmp_gt_u32 s2, 31
	s_cselect_b32 s20, 9, 8
	s_lshl_b64 s[10:11], s[38:39], 19
	s_lshl_b32 s14, s20, 19
	s_add_u32 s8, s8, s14
	s_addc_u32 s9, s9, 0
	s_add_u32 s6, s8, 0xe900000
	s_addc_u32 s7, s9, 0
	s_add_i32 s21, s19, 0
	v_lshl_add_u32 v144, v2, 11, v1
	s_add_i32 m0, s21, 0x10000
	v_mov_b32_e32 v131, v145
	global_load_lds_dwordx4 v144, s[6:7]
	s_add_i32 m0, s21, 0x12000
	s_add_u32 s8, s8, 0xe940000
	global_load_lds_dwordx4 v130, s[6:7]
	s_addc_u32 s9, s9, 0
	s_add_i32 m0, s21, 0x14000
	v_mov_b32_e32 v135, v145
	global_load_lds_dwordx4 v144, s[8:9]
	s_add_i32 m0, s21, 0x16000
	s_add_u32 s15, s4, s10
	s_addc_u32 s23, s5, s11
	global_load_lds_dwordx4 v130, s[8:9]
	s_add_u32 s8, s15, 0x1000000
	s_addc_u32 s9, s23, 0
	s_add_i32 s22, s21, 0x2000
	v_cmp_eq_u32_e32 vcc, 0, v147
	s_and_saveexec_b64 s[100:101], vcc
	s_cbranch_execz .Lgw_skip_gm
	v_readlane_b32 s56, v255, 54
	v_readlane_b32 s57, v255, 55
	v_readlane_b32 s58, v255, 50
	v_readlane_b32 s59, v255, 51
	v_readlane_b32 s60, v255, 52
	v_readlane_b32 s61, v255, 53
	s_mov_b32 s62, 0
	s_nop 1
	v_mov_b32_e32 v20, s58
	v_mov_b32_e32 v21, s60
	s_nop 1

.Lgw_skip_gm:
	s_or_b64 exec, exec, s[100:101]
	s_waitcnt vmcnt(4)
	s_barrier
	s_mov_b32 m0, s21
	s_add_u32 s26, s15, 0x1040000
	global_load_lds_dwordx4 v134, s[8:9]
	s_mov_b32 m0, s22
	s_addc_u32 s27, s23, 0
	s_add_i32 s23, s21, 0x4000
	global_load_lds_dwordx4 v132, s[8:9]
	s_mov_b32 m0, s23
	s_add_i32 s25, s21, 0x6000
	global_load_lds_dwordx4 v134, s[26:27]
	s_mov_b32 m0, s25
	v_mov_b32_e32 v133, v145
	global_load_lds_dwordx4 v132, s[26:27]
	v_lshl_add_u64 v[6:7], s[6:7], 0, v[144:145]
	v_lshl_add_u64 v[4:5], s[6:7], 0, v[130:131]
	v_lshl_add_u64 v[2:3], s[8:9], 0, v[134:135]
	s_cmp_lg_u32 s13, 1
	v_lshl_add_u64 v[0:1], s[8:9], 0, v[132:133]
	s_cbranch_scc1 .LBB0_996
	s_barrier
